# NORM rows: gain vector loaded once per phase, adaLN shift/scale vectors cached in registers per modulation row, base pointers preloaded; x loads are the only per-row loads
# speedup vs baseline: 1.2447x; 1.0142x over previous
; __device__ __forceinline__ int ltid() { int t = threadIdx.x; asm volatile("" : "+v"(t)); return t; }
; __device__ __forceinline__ void ph_norm(const P& p, int layer, char* smem) {
;   const int tid = ltid(), lane = tid & 63, wid = tid >> 6;
;   const int nprep = layer > 0 ? prep_count(layer) : 0; const int kind = layer % 3;
;   const int nzero = kind == 1 ? 8320 : 0;
;   (void)nzero;
;   for (int it = blockIdx.x; it < nprep + 4160; it += gridDim.x) {
;     if (it < nprep) { prep_item(p, layer, it, (float*)smem); continue; }
;     int row = (it - nprep) * 8 + wid; int mo; const float* xr = xrowp(p, row, mo);
;     float4 v[4]; float ss = 0.f;
; #pragma unroll
;     for (int i = 0; i < 4; i++) { v[i] = *(const float4*)(xr + lane * 4 + 256 * i); ss += v[i].x * v[i].x + v[i].y * v[i].y + v[i].z * v[i].z + v[i].w * v[i].w; }
;     ss = wsum(ss); float rs = rsqrtf(ss * (1.f / 1024.f) + 1e-6f);
;     const float* g = p.norm_g + (size_t)layer * 1024; const float* md = p.MOD + (size_t)(layer * 3 + mo) * 3072;
; #pragma unroll
;     for (int i = 0; i < 4; i++) { int cidx = lane * 4 + 256 * i; float4 gg = *(const float4*)(g + cidx), sh = *(const float4*)(md + cidx), sc = *(const float4*)(md + 1024 + cidx);
.LBB0_1731:
	v_readlane_b32 s6, v254, 57
	v_readlane_b32 s52, v254, 59
	v_readlane_b32 s7, v254, 58
	s_mov_b32 s54, s6
	s_mul_i32 s6, s6, 3
	v_readlane_b32 s53, v254, 60
	s_sub_i32 s76, s53, s6
	s_ashr_i32 s7, s53, 31
	s_mov_b32 s6, s53
	s_lshl_b64 s[6:7], s[6:7], 12
	s_cmp_eq_u32 s76, 2
	s_cselect_b32 s77, 11, 10
	s_ashr_i32 s55, s54, 31
	v_readlane_b32 s60, v254, 9
	s_lshl_b64 s[8:9], s[54:55], 23
	s_lshl_b32 s78, s54, 1
	s_lshl_b64 s[30:31], s[54:55], 22
	s_lshl_b64 s[40:41], s[54:55], 24
	v_readlane_b32 s68, v254, 17
	v_lshlrev_b32_e32 v0, 2, v4
	v_readlane_b32 s61, v254, 10
	v_readlane_b32 s62, v254, 11
	v_readlane_b32 s63, v254, 12
	v_readlane_b32 s64, v254, 13
	v_readlane_b32 s65, v254, 14
	v_readlane_b32 s66, v254, 15
	v_readlane_b32 s67, v254, 16
	v_readlane_b32 s69, v254, 18
	v_readlane_b32 s70, v254, 19
	v_readlane_b32 s71, v254, 20
	v_readlane_b32 s72, v254, 21
	v_readlane_b32 s73, v254, 22
	v_readlane_b32 s74, v254, 23
	v_readlane_b32 s75, v254, 24
	s_add_u32 s6, s68, s6
	v_and_b32_e32 v8, 0xfc, v0
	s_addc_u32 s7, s69, s7
	v_lshlrev_b32_e32 v0, 2, v8
	v_readlane_b32 s60, v254, 25
	s_waitcnt lgkmcnt(0)
	v_lshl_add_u64 v[2:3], s[6:7], 0, v[0:1]
	s_mul_i32 s6, s54, 0x1820000
	v_readlane_b32 s74, v254, 39
	s_mul_hi_i32 s7, s54, 0x1820000
	v_readlane_b32 s75, v254, 40
	s_add_u32 s6, s74, s6
	v_readlane_b32 s44, v253, 49
	s_addc_u32 s7, s75, s7
	v_readlane_b32 s48, v253, 53
	v_readlane_b32 s49, v253, 54
	s_add_u32 s8, s48, s8
	v_readlane_b32 s72, v254, 37
	s_addc_u32 s9, s49, s9
	s_mul_i32 s10, s54, 0x500000
	v_readlane_b32 s73, v254, 38
	s_mul_hi_i32 s11, s54, 0x500000
	s_add_u32 s10, s72, s10
	s_addc_u32 s11, s73, s11
	s_mul_i32 s12, s54, 0xa00000
	v_readlane_b32 s61, v254, 26
	v_readlane_b32 s62, v254, 27
	v_readlane_b32 s63, v254, 28
	v_readlane_b32 s64, v254, 29
	v_readlane_b32 s65, v254, 30
	v_readlane_b32 s66, v254, 31
	v_readlane_b32 s67, v254, 32
	v_readlane_b32 s68, v254, 33
	v_readlane_b32 s69, v254, 34
	v_readlane_b32 s70, v254, 35
	v_readlane_b32 s71, v254, 36
	s_mul_hi_i32 s13, s54, 0xa00000
	s_add_u32 s12, s60, s12
	s_addc_u32 s13, s61, s13
	v_readlane_b32 s60, v253, 57
	v_readlane_b32 s70, v254, 3
	v_readlane_b32 s71, v254, 4
	s_add_u32 s30, s70, s30
	v_readlane_b32 s46, v253, 51
	v_readlane_b32 s50, v253, 55
	s_addc_u32 s31, s71, s31
	s_mul_i32 s42, s54, 0x6000
	v_readlane_b32 s47, v253, 52
	v_readlane_b32 s51, v253, 56
	s_mul_hi_i32 s28, s54, 0x6000
	s_add_u32 s46, s50, s42
	s_addc_u32 s47, s51, s28
	v_readlane_b32 s48, v253, 41
	v_readlane_b32 s49, v253, 42
	s_add_u32 s79, s48, s40
	v_readlane_b32 s50, v253, 43
	v_readlane_b32 s51, v253, 44
	s_addc_u32 s80, s49, s41
	s_lshl_b64 s[40:41], s[54:55], 19
	v_readlane_b32 s42, v253, 37
	v_readlane_b32 s43, v253, 38
	s_add_u32 s81, s42, s40
	v_readlane_b32 s48, v253, 45
	v_readlane_b32 s74, v254, 7
	s_addc_u32 s82, s43, s41
	v_readlane_b32 s50, v253, 47
	v_readlane_b32 s75, v254, 8
	v_readlane_b32 s51, v253, 48
	s_add_u32 s74, s50, s40
	s_waitcnt vmcnt(0)
	v_ashrrev_i32_e32 v28, 6, v4
	v_readlane_b32 s28, v253, 12
	s_addc_u32 s75, s51, s41
	v_readlane_b32 s64, v253, 61
	v_add_u32_e32 v0, s28, v28
	s_lshl_b32 s28, s18, 3
	v_readlane_b32 s65, v253, 62
	v_readlane_b32 s66, v253, 63
	v_readlane_b32 s67, v254, 0
	v_readlane_b32 s68, v254, 1
	v_readlane_b32 s69, v254, 2
	v_subrev_u32_e32 v4, s28, v0
	v_or_b32_e32 v10, 0x100, v8
	v_or_b32_e32 v12, 0x200, v8
	v_or_b32_e32 v14, 0x300, v8
	v_lshlrev_b32_e32 v0, 1, v8
	v_lshl_add_u64 v[6:7], s[24:25], 0, v[0:1]
	v_lshlrev_b32_e32 v8, 2, v8
	v_lshlrev_b32_e32 v10, 2, v10
	v_lshlrev_b32_e32 v12, 2, v12
	v_lshlrev_b32_e32 v14, 2, v14
	s_mul_i32 s83, s53, 3
	s_lshl_b32 s64, s96, 6
	s_lshl_b32 s65, s96, 2
	s_lshl_b32 s66, s96, 1
	v_readlane_b32 s67, v253, 25
	v_readlane_b32 s68, v253, 24
	v_readlane_b32 s69, v253, 23
	s_mov_b32 s70, s84
	v_readlane_b32 s45, v253, 50
	v_readlane_b32 s61, v253, 58
	v_readlane_b32 s62, v253, 59
	v_readlane_b32 s63, v253, 60
	v_readlane_b32 s72, v254, 5
	v_readlane_b32 s73, v254, 6
	v_readlane_b32 s49, v253, 46
	v_mov_b32_e32 v236, -1
	global_load_dwordx4 v[188:191], v[2:3], off
	global_load_dwordx4 v[192:195], v[2:3], off offset:1024
	global_load_dwordx4 v[196:199], v[2:3], off offset:2048
	global_load_dwordx4 v[200:203], v[2:3], off offset:3072
	v_readlane_b32 s42, v254, 49
	v_readlane_b32 s43, v254, 50
	s_nop 4
	global_load_dwordx2 v[238:239], v1, s[42:43]
	v_readlane_b32 s42, v251, 8
	v_readlane_b32 s43, v251, 9
	s_nop 4
	global_load_dwordx2 v[240:241], v1, s[42:43]
	s_waitcnt vmcnt(0)
	s_branch .LBB0_1734

; __device__ __forceinline__ void store4b(bfr* dst, f32x4 v) { uint2 u; u.x = pk2(v[0], v[1]); u.y = pk2(v[2], v[3]); *(uint2*)dst = u; }
; __device__ __forceinline__ float* xrowp(const P& p, int row, int& mi) {
;   int b = row / BT_, o = row - b * BT_;
;   if (o < 256) { mi = 2; return p.Xc + (size_t)(b * 256 + o) * 1024; }
;   mi = b; return p.Xx + (size_t)(b * 16384 + o - 256) * 1024;
; }
; __device__ __forceinline__ void ph_norm(const P& p, int layer, char* smem) {
;     ...
;   for (int it = blockIdx.x; it < nprep + 4160; it += gridDim.x) {
;     if (it < nprep) { prep_item(p, layer, it, (float*)smem); continue; }
;     int row = (it - nprep) * 8 + wid; int mo; const float* xr = xrowp(p, row, mo);
;     float4 v[4]; float ss = 0.f;
; #pragma unroll
;     for (int i = 0; i < 4; i++) { v[i] = *(const float4*)(xr + lane * 4 + 256 * i); ss += v[i].x * v[i].x + v[i].y * v[i].y + v[i].z * v[i].z + v[i].w * v[i].w; }
;     ss = wsum(ss); float rs = rsqrtf(ss * (1.f / 1024.f) + 1e-6f);
;     const float* g = p.norm_g + (size_t)layer * 1024; const float* md = p.MOD + (size_t)(layer * 3 + mo) * 3072;
; #pragma unroll
;     for (int i = 0; i < 4; i++) { int cidx = lane * 4 + 256 * i; float4 gg = *(const float4*)(g + cidx), sh = *(const float4*)(md + cidx), sc = *(const float4*)(md + 1024 + cidx);
;       f32x4 o; o[0] = v[i].x * rs * gg.x * (1.f + sc.x) + sh.x; o[1] = v[i].y * rs * gg.y * (1.f + sc.y) + sh.y; o[2] = v[i].z * rs * gg.z * (1.f + sc.z) + sh.z; o[3] = v[i].w * rs * gg.w * (1.f + sc.w) + sh.w;
;       store4b(p.H + (size_t)row * (kind == 2 ? 2048 : 1024) + cidx, o); }
;   }
.LBB0_1734:
	s_cmp_ge_i32 s70, s18
	s_mov_b64 s[40:41], -1
	s_cbranch_scc0 .LBB0_1740
	s_mov_b32 s28, 0x7e07e07f
	v_mul_hi_i32 v0, v4, s28
	v_lshrrev_b32_e32 v5, 31, v0
	v_ashrrev_i32_e32 v0, 13, v0
	v_add_u32_e32 v0, v0, v5
	s_movk_i32 s28, 0xbf00
	v_mad_i32_i24 v9, v0, s28, v4
	v_mul_i32_i24_e32 v5, 0xffffbf00, v0
	v_cmp_lt_i32_e32 vcc, s15, v9
	s_and_saveexec_b64 s[40:41], vcc
	s_xor_b64 s[40:41], exec, s[40:41]
	v_lshl_add_u32 v5, v0, 14, v5
	s_movk_i32 s28, 0xff00
	v_add3_u32 v16, v4, v5, s28
	s_or_saveexec_b64 s[40:41], s[40:41]
	v_mov_b64_e32 v[18:19], v[238:239]
	s_xor_b64 exec, exec, s[40:41]
	s_cbranch_execz .LBB0_1739
	s_sub_i32 s28, s70, s18
	v_readlane_b32 s42, v251, 8
	v_lshl_add_u32 v9, s28, 3, v28
	v_lshlrev_b32_e32 v0, 8, v0
	v_readlane_b32 s43, v251, 9
	v_add3_u32 v16, v5, v9, v0
	v_mov_b32_e32 v0, 2
	v_mov_b64_e32 v[18:19], v[240:241]
.LBB0_1739:
	s_or_b64 exec, exec, s[40:41]
	v_ashrrev_i32_e32 v17, 31, v16
	v_lshlrev_b64 v[16:17], 12, v[16:17]
	v_mov_b32_e32 v9, v1
	v_cmp_ne_u32_e32 vcc, v0, v236
	s_cbranch_vccz .Lnorm_cached
	v_mov_b32_e32 v236, v0
	v_add_u32_e32 v0, s83, v0
	v_mov_b64_e32 v[34:35], s[20:21]
	s_movk_i32 s28, 0x3000
	v_mad_i64_i32 v[42:43], s[40:41], v0, s28, v[34:35]
	s_mov_b64 s[40:41], 0x1000
	v_lshl_add_u64 v[48:49], v[42:43], 0, v[8:9]
	v_lshl_add_u64 v[34:35], v[48:49], 0, s[40:41]
	global_load_dwordx4 v[204:207], v[34:35], off
	global_load_dwordx4 v[208:211], v[34:35], off offset:1024
	global_load_dwordx4 v[212:215], v[34:35], off offset:2048
	global_load_dwordx4 v[216:219], v[34:35], off offset:3072
	global_load_dwordx4 v[220:223], v[48:49], off
	global_load_dwordx4 v[224:227], v[48:49], off offset:1024
	global_load_dwordx4 v[228:231], v[48:49], off offset:2048
	global_load_dwordx4 v[232:235], v[48:49], off offset:3072
	s_waitcnt vmcnt(0)
	v_pk_add_f32 v[204:205], v[204:205], 1.0 op_sel_hi:[1,0]
	v_pk_add_f32 v[206:207], v[206:207], 1.0 op_sel_hi:[1,0]
	v_pk_add_f32 v[208:209], v[208:209], 1.0 op_sel_hi:[1,0]
	v_pk_add_f32 v[210:211], v[210:211], 1.0 op_sel_hi:[1,0]
	v_pk_add_f32 v[212:213], v[212:213], 1.0 op_sel_hi:[1,0]
	v_pk_add_f32 v[214:215], v[214:215], 1.0 op_sel_hi:[1,0]
	v_pk_add_f32 v[216:217], v[216:217], 1.0 op_sel_hi:[1,0]
	v_pk_add_f32 v[218:219], v[218:219], 1.0 op_sel_hi:[1,0]
.Lnorm_cached:
	v_ashrrev_i32_e32 v5, 31, v4
	v_lshlrev_b64 v[50:51], s77, v[4:5]
	v_lshl_add_u64 v[50:51], v[50:51], 1, v[6:7]
	s_mov_b64 s[40:41], 0
	v_lshl_add_u64 v[16:17], v[18:19], 0, v[16:17]
	v_lshl_add_u64 v[30:31], v[16:17], 0, v[8:9]
	global_load_dwordx4 v[16:19], v[30:31], off
	global_load_dwordx4 v[20:23], v[30:31], off offset:1024
	global_load_dwordx4 v[24:27], v[30:31], off offset:2048
	s_nop 0
	global_load_dwordx4 v[30:33], v[30:31], off offset:3072
	s_waitcnt vmcnt(0)
	v_mov_b32_e32 v58, v17
	v_mov_b32_e32 v59, v21
	v_mov_b32_e32 v56, v16
	v_mov_b32_e32 v57, v20
	v_mov_b32_e32 v66, v25
	v_mov_b32_e32 v67, v31
	v_pk_mul_f32 v[58:59], v[58:59], v[58:59]
	v_mov_b32_e32 v52, v18
	v_mov_b32_e32 v53, v22
	v_mov_b32_e32 v64, v24
	v_mov_b32_e32 v65, v30
	v_pk_mul_f32 v[66:67], v[66:67], v[66:67]
	v_pk_fma_f32 v[56:57], v[56:57], v[56:57], v[58:59]
	v_mov_b32_e32 v54, v19
	v_mov_b32_e32 v55, v23
	v_mov_b32_e32 v60, v26
	v_mov_b32_e32 v61, v32
	v_pk_fma_f32 v[58:59], v[64:65], v[64:65], v[66:67]
	v_pk_fma_f32 v[52:53], v[52:53], v[52:53], v[56:57]
	v_mov_b32_e32 v62, v27
	v_mov_b32_e32 v63, v33
	v_pk_fma_f32 v[56:57], v[60:61], v[60:61], v[58:59]
	v_pk_fma_f32 v[52:53], v[54:55], v[54:55], v[52:53]
	v_pk_fma_f32 v[54:55], v[62:63], v[62:63], v[56:57]
	v_add_f32_e32 v5, v52, v53
	v_add_f32_e32 v5, v5, v54
	v_add_f32_e32 v5, v5, v55
	s_nop 1
	v_add_f32_dpp v5, v5, v5 quad_perm:[1,0,3,2] row_mask:0xf bank_mask:0xf bound_ctrl:1
	s_nop 0
	s_nop 1
	v_add_f32_dpp v5, v5, v5 quad_perm:[2,3,0,1] row_mask:0xf bank_mask:0xf bound_ctrl:1
	s_nop 1
	s_nop 1
	v_add_f32_dpp v5, v5, v5 row_half_mirror row_mask:0xf bank_mask:0xf bound_ctrl:1
	s_nop 1
	s_nop 1
	v_add_f32_dpp v5, v5, v5 row_mirror row_mask:0xf bank_mask:0xf bound_ctrl:1
	s_nop 1
	s_nop 1
	v_mov_b32_dpp v0, v5 row_bcast:15 row_mask:0xa bank_mask:0xf
	v_add_f32_e32 v0, v5, v0
	s_nop 1
	s_nop 1
	v_mov_b32_dpp v9, v0 row_bcast:31 row_mask:0xc bank_mask:0xf
	v_add_f32_e32 v0, v0, v9
	s_nop 0
	v_readlane_b32 s28, v0, 63
	s_nop 1
	v_fma_f32 v0, s28, v173, v169
	s_mov_b32 s28, 0x800000
	v_mul_f32_e32 v5, 0x4b800000, v0
	v_cmp_gt_f32_e32 vcc, s28, v0
	s_nop 1
	v_cndmask_b32_e32 v0, v0, v5, vcc
	v_rsq_f32_e32 v0, v0
	s_nop 0
	v_mul_f32_e32 v5, 0x45800000, v0
	v_cndmask_b32_e32 v0, v0, v5, vcc
	v_pk_mul_f32 v[16:17], v[16:17], v[0:1] op_sel_hi:[1,0]
	v_pk_mul_f32 v[18:19], v[18:19], v[0:1] op_sel_hi:[1,0]
	v_pk_mul_f32 v[20:21], v[20:21], v[0:1] op_sel_hi:[1,0]
	v_pk_mul_f32 v[22:23], v[22:23], v[0:1] op_sel_hi:[1,0]
	v_pk_mul_f32 v[24:25], v[24:25], v[0:1] op_sel_hi:[1,0]
	v_pk_mul_f32 v[26:27], v[26:27], v[0:1] op_sel_hi:[1,0]
	v_pk_mul_f32 v[30:31], v[30:31], v[0:1] op_sel_hi:[1,0]
	v_pk_mul_f32 v[32:33], v[32:33], v[0:1] op_sel_hi:[1,0]
	v_pk_mul_f32 v[16:17], v[188:189], v[16:17]
	v_pk_mul_f32 v[18:19], v[190:191], v[18:19]
	v_pk_fma_f32 v[16:17], v[16:17], v[204:205], v[220:221]
	v_pk_fma_f32 v[18:19], v[18:19], v[206:207], v[222:223]
	v_cvt_pk_bf16_f32 v16, v16, v17
	v_cvt_pk_bf16_f32 v17, v18, v19
	global_store_dwordx2 v[50:51], v[16:17], off
	v_pk_mul_f32 v[20:21], v[192:193], v[20:21]
	v_pk_mul_f32 v[22:23], v[194:195], v[22:23]
	v_pk_fma_f32 v[20:21], v[20:21], v[208:209], v[224:225]
	v_pk_fma_f32 v[22:23], v[22:23], v[210:211], v[226:227]
	v_cvt_pk_bf16_f32 v20, v20, v21
	v_cvt_pk_bf16_f32 v21, v22, v23
	global_store_dwordx2 v[50:51], v[20:21], off offset:512
	v_pk_mul_f32 v[24:25], v[196:197], v[24:25]
	v_pk_mul_f32 v[26:27], v[198:199], v[26:27]
	v_pk_fma_f32 v[24:25], v[24:25], v[212:213], v[228:229]
	v_pk_fma_f32 v[26:27], v[26:27], v[214:215], v[230:231]
	v_cvt_pk_bf16_f32 v24, v24, v25
	v_cvt_pk_bf16_f32 v25, v26, v27
	global_store_dwordx2 v[50:51], v[24:25], off offset:1024
	v_pk_mul_f32 v[30:31], v[200:201], v[30:31]
	v_pk_mul_f32 v[32:33], v[202:203], v[32:33]
	v_pk_fma_f32 v[30:31], v[30:31], v[216:217], v[232:233]
	v_pk_fma_f32 v[32:33], v[32:33], v[218:219], v[234:235]
	v_cvt_pk_bf16_f32 v30, v30, v31
	v_cvt_pk_bf16_f32 v31, v32, v33
	global_store_dwordx2 v[50:51], v[30:31], off offset:1536
